# P1 epilogue bias staged to LDS by one DMA per unit (wave 0), epilogue reads bias via ds_read instead of global loads
# speedup vs baseline: 1.0044x; 1.0044x over previous
.LBB0_378:
	s_lshl_b32 s65, s3, 6
	s_and_b32 s1, s1, 3
	v_or_b32_e32 v6, s65, v3
	v_lshlrev_b32_e32 v6, 7, v6
	s_lshl_b32 s3, s1, 5
	v_or_b32_e32 v8, v6, v192
	v_or_b32_e32 v9, v6, v193
	v_or_b32_e32 v6, s3, v3
	v_lshlrev_b32_e32 v6, 7, v6
	s_mov_b64 s[48:49], 0x80
	v_or_b32_e32 v10, v6, v192
	v_or_b32_e32 v11, v6, v193
	v_lshl_add_u64 v[6:7], v[4:5], 0, s[48:49]
	s_add_i32 m0, s79, 0x18000
	s_mov_b64 s[50:51], 0x40080
	s_waitcnt vmcnt(2)
	s_barrier
	global_load_lds_dwordx4 v[6:7], off
	v_lshl_add_u64 v[6:7], v[4:5], 0, s[50:51]
	s_add_i32 m0, s79, 0x1a000
	s_mov_b64 s[52:53], 0x10080
	global_load_lds_dwordx4 v[6:7], off
	v_lshl_add_u64 v[6:7], v[4:5], 0, s[52:53]
	s_add_i32 m0, s79, 0x1c000
	s_mov_b64 s[54:55], 0x50080
	global_load_lds_dwordx4 v[6:7], off
	v_lshl_add_u64 v[4:5], v[4:5], 0, s[54:55]
	s_add_i32 m0, s79, 0x1e000
	v_writelane_b32 v254, s34, 25
	global_load_lds_dwordx4 v[4:5], off
	s_nop 0
	v_writelane_b32 v254, s35, 26
	v_writelane_b32 v254, s26, 27
	s_mov_b32 s98, s0
	s_cmpk_lt_u32 s0, 0x100
	v_or_b32_e32 v4, s3, v191
	v_writelane_b32 v254, s27, 28
	s_cselect_b64 s[56:57], -1, 0
	s_lshl_b32 s85, s1, 6
	s_ashr_i32 s3, s33, 31
	s_ashr_i32 s73, s2, 31
	v_readlane_b32 s0, v254, 13
	v_readlane_b32 s1, v254, 14
	s_add_u32 s58, s0, 0x783800
	s_addc_u32 s59, s1, 0
	s_add_u32 s60, s0, 0x784800
	s_mov_b32 s13, 0x14800
	s_addc_u32 s61, s1, 0
	s_addk_i32 s13, 0x100
	s_mov_b32 s12, 0x10800
	v_add_u32_e32 v205, s13, v10
	v_add_u32_e32 v206, s13, v11
	s_mov_b32 s13, 0x18800
	s_addk_i32 s12, 0x100
	s_addk_i32 s13, 0x100
	s_mov_b32 s8, 0x18000
	s_mov_b32 s9, 0x1c000
	s_waitcnt vmcnt(4)
	s_mov_b32 s1, 0x10000
	v_add_u32_e32 v201, s12, v10
	v_add_u32_e32 v202, s12, v11
	s_mov_b32 s12, 0x14000
	v_add_u32_e32 v209, s13, v10
	v_add_u32_e32 v210, s13, v11
	s_mov_b32 s13, 0x1c800
	v_lshlrev_b32_e32 v160, 1, v191
	s_addk_i32 s1, 0x100
	s_addk_i32 s12, 0x100
	s_addk_i32 s13, 0x100
	s_movk_i32 s68, 0xfc40
	s_movk_i32 s92, 0xa040
	s_add_i32 s70, s8, 0x100
	s_add_i32 s71, s9, 0x100
	v_or_b32_e32 v198, 0xfffff900, v4
	v_cmp_gt_u32_e64 s[6:7], 8, v3
	v_lshl_add_u64 v[162:163], s[42:43], 0, v[160:161]
	v_lshl_add_u64 v[164:165], s[34:35], 0, v[160:161]
	v_lshl_add_u64 v[166:167], s[26:27], 0, v[160:161]
	v_add_u32_e32 v168, v194, v186
	v_mov_b32_e32 v169, v161
	s_mov_b32 s0, 0
	v_mov_b64_e32 v[170:171], 0x580
	v_mov_b64_e32 v[172:173], 0x57f
	v_add_u32_e32 v199, s1, v10
	v_add_u32_e32 v200, s1, v11
	v_add_u32_e32 v203, s12, v10
	v_add_u32_e32 v204, s12, v11
	v_add_u32_e32 v207, 0x100, v8
	v_add_u32_e32 v208, 0x100, v9
	v_add_u32_e32 v211, s13, v10
	v_add_u32_e32 v212, s13, v11
	s_movk_i32 s13, 0xc00
	s_mov_b32 s69, -1
	s_mov_b32 s72, 0x3e000000
	s_mov_b32 s93, -1
	v_add_u32_e32 v213, s70, v10
	v_add_u32_e32 v214, s70, v11
	v_add_u32_e32 v215, s71, v10
	v_add_u32_e32 v216, s71, v11
	s_barrier
	s_branch .LBB0_381

.LBB0_383:
	s_ashr_i32 s67, s66, 31
	s_lshl_b64 s[26:27], s[66:67], 19
	s_add_u32 s26, s40, s26
	s_addc_u32 s27, s41, s27
	s_and_b64 s[34:35], s[8:9], exec
	s_cselect_b32 s34, s27, s5
	s_cselect_b32 s35, s26, s4
	s_ashr_i32 s29, s28, 31
	s_lshl_b64 s[38:39], s[28:29], 19
	s_add_u32 s62, s10, s38
	s_addc_u32 s63, s11, s39
	s_and_b64 s[38:39], s[8:9], exec
	s_cselect_b32 s29, s63, s83
	s_cselect_b32 s38, s62, s82
	s_add_u32 s39, s82, 0x100
	s_addc_u32 s67, s83, 0
	s_mov_b32 s94, -2
	s_mov_b64 vcc, 0
	v_lshl_add_u64 v[132:133], s[4:5], 0, v[168:169]
	ds_read_b128 v[134:137], v199
	ds_read_b128 v[138:141], v200
	ds_read_b128 v[142:145], v201
	ds_read_b128 v[146:149], v202
	ds_read_b128 v[150:153], v203
	ds_read_b128 v[174:177], v204
	ds_read_b128 v[178:181], v205
	ds_read_b128 v[182:185], v206
	s_add_u32 s24, s4, vcc_lo
	s_addc_u32 s25, s5, vcc_hi
	s_add_u32 s24, s24, 0x100
	s_addc_u32 s25, s25, 0
	s_add_u32 s82, s39, vcc_lo
	s_addc_u32 s83, s67, vcc_hi
	s_cmpk_eq_i32 vcc_lo, 0x700
	s_cselect_b32 s87, s29, s83
	s_cselect_b32 s86, s38, s82
	s_cselect_b32 s83, s34, s25
	s_cselect_b32 s82, s35, s24
	v_lshl_add_u64 v[154:155], v[132:133], 0, vcc
	v_lshl_add_u64 v[250:251], v[154:155], 0, s[48:49]
	s_add_i32 m0, s79, 0x8000
	s_mov_b64 s[24:25], 0x20080
	ds_read_b128 v[218:221], v207
	ds_read_b128 v[222:225], v207 offset:2048
	ds_read_b128 v[226:229], v208
	ds_read_b128 v[230:233], v208 offset:2048
	ds_read_b128 v[234:237], v207 offset:4096
	ds_read_b128 v[238:241], v207 offset:6144
	ds_read_b128 v[242:245], v208 offset:4096
	ds_read_b128 v[246:249], v208 offset:6144
	global_load_lds_dwordx4 v[250:251], off
	v_lshl_add_u64 v[250:251], v[154:155], 0, s[24:25]
	s_add_i32 m0, s79, 0xa000
	s_mov_b64 s[24:25], 0x60080
	global_load_lds_dwordx4 v[250:251], off
	v_lshl_add_u64 v[250:251], v[154:155], 0, s[50:51]
	s_add_i32 m0, s79, 0xc000
	v_lshl_add_u64 v[154:155], v[154:155], 0, s[24:25]
	global_load_lds_dwordx4 v[250:251], off
	s_add_i32 m0, s79, 0xe000
	s_nop 0
	global_load_lds_dwordx4 v[154:155], off
	s_waitcnt lgkmcnt(0)
	s_barrier
	s_cmp_lg_u32 s98, 0
	s_cbranch_scc1 .Lp1b_skip
	v_mbcnt_lo_u32_b32 v255, -1, 0
	v_mbcnt_hi_u32_b32 v255, -1, v255
	s_cmp_gt_i32 s96, 13
	s_cbranch_scc1 .Lp1b_gate
	s_lshl_b32 s100, s96, 10
	s_add_u32 s100, s90, s100
	s_addc_u32 s101, s91, 0
	v_lshlrev_b32_e32 v255, 4, v255
	s_branch .Lp1b_issue
.Lp1b_gate:
	s_lshl_b32 s100, s96, 9
	s_add_i32 s100, s100, 0xffffe400
	s_add_u32 s100, s58, s100
	s_addc_u32 s101, s59, 0
	v_lshlrev_b32_e32 v255, 4, v255
	s_mov_b32 exec_lo, 0
	v_add_u32_e32 v255, 0xe00, v255
	s_mov_b32 exec_lo, -1
.Lp1b_issue:
	s_mov_b32 m0, 0x27500
	s_nop 0
	global_load_lds_dwordx4 v255, s[100:101]
.Lp1b_skip:
	v_mfma_f32_16x16x32_bf16 v[128:131], v[134:137], v[218:221], 0
	v_mfma_f32_16x16x32_bf16 v[128:131], v[138:141], v[226:229], v[128:131]
	v_mfma_f32_16x16x32_bf16 v[112:115], v[134:137], v[222:225], 0
	v_mfma_f32_16x16x32_bf16 v[112:115], v[138:141], v[230:233], v[112:115]
	v_mfma_f32_16x16x32_bf16 v[96:99], v[134:137], v[234:237], 0
	v_mfma_f32_16x16x32_bf16 v[96:99], v[138:141], v[242:245], v[96:99]
	v_mfma_f32_16x16x32_bf16 v[80:83], v[134:137], v[238:241], 0
	v_mfma_f32_16x16x32_bf16 v[80:83], v[138:141], v[246:249], v[80:83]
	v_mfma_f32_16x16x32_bf16 v[76:79], v[142:145], v[238:241], 0
	v_mfma_f32_16x16x32_bf16 v[76:79], v[146:149], v[246:249], v[76:79]
	v_mfma_f32_16x16x32_bf16 v[92:95], v[142:145], v[234:237], 0
	v_mfma_f32_16x16x32_bf16 v[92:95], v[146:149], v[242:245], v[92:95]
	v_mfma_f32_16x16x32_bf16 v[108:111], v[142:145], v[222:225], 0
	v_mfma_f32_16x16x32_bf16 v[108:111], v[146:149], v[230:233], v[108:111]
	v_mfma_f32_16x16x32_bf16 v[124:127], v[142:145], v[218:221], 0
	v_mfma_f32_16x16x32_bf16 v[124:127], v[146:149], v[226:229], v[124:127]
	v_mfma_f32_16x16x32_bf16 v[120:123], v[150:153], v[218:221], 0
	v_mfma_f32_16x16x32_bf16 v[120:123], v[174:177], v[226:229], v[120:123]
	v_mfma_f32_16x16x32_bf16 v[104:107], v[150:153], v[222:225], 0
	v_mfma_f32_16x16x32_bf16 v[104:107], v[174:177], v[230:233], v[104:107]
	v_mfma_f32_16x16x32_bf16 v[88:91], v[150:153], v[234:237], 0
	v_mfma_f32_16x16x32_bf16 v[88:91], v[174:177], v[242:245], v[88:91]
	v_mfma_f32_16x16x32_bf16 v[72:75], v[150:153], v[238:241], 0
	v_mfma_f32_16x16x32_bf16 v[72:75], v[174:177], v[246:249], v[72:75]
	v_mfma_f32_16x16x32_bf16 v[68:71], v[178:181], v[238:241], 0
	v_mfma_f32_16x16x32_bf16 v[68:71], v[182:185], v[246:249], v[68:71]
	v_mfma_f32_16x16x32_bf16 v[84:87], v[178:181], v[234:237], 0
	v_mfma_f32_16x16x32_bf16 v[84:87], v[182:185], v[242:245], v[84:87]
	v_mfma_f32_16x16x32_bf16 v[100:103], v[178:181], v[222:225], 0
	v_mfma_f32_16x16x32_bf16 v[100:103], v[182:185], v[230:233], v[100:103]
	v_mfma_f32_16x16x32_bf16 v[116:119], v[178:181], v[218:221], 0
	v_mfma_f32_16x16x32_bf16 v[116:119], v[182:185], v[226:229], v[116:119]
	s_barrier
	s_add_i32 s24, s1, s77
	v_lshl_add_u64 v[154:155], s[86:87], 0, v[158:159]
	s_mov_b32 m0, s24
	ds_read_b128 v[218:221], v207 offset:16384
	ds_read_b128 v[222:225], v207 offset:18432
	ds_read_b128 v[226:229], v208 offset:16384
	ds_read_b128 v[230:233], v208 offset:18432
	ds_read_b128 v[234:237], v207 offset:20480
	ds_read_b128 v[238:241], v207 offset:22528
	ds_read_b128 v[242:245], v208 offset:20480
	ds_read_b128 v[246:249], v208 offset:22528
	global_load_lds_dwordx4 v[154:155], off
	v_lshl_add_u64 v[250:251], v[154:155], 0, s[14:15]
	s_add_i32 m0, s24, 0x2000
	s_add_i32 s24, s12, s77
	global_load_lds_dwordx4 v[250:251], off
	v_lshl_add_u64 v[250:251], v[154:155], 0, s[16:17]
	s_mov_b32 m0, s24
	s_nop 0
	global_load_lds_dwordx4 v[250:251], off
	v_lshl_add_u64 v[250:251], v[154:155], 0, s[18:19]
	s_add_i32 m0, s24, 0x2000
	s_nop 0
	global_load_lds_dwordx4 v[250:251], off
	s_waitcnt vmcnt(4)
	s_waitcnt lgkmcnt(0)
	s_barrier
	v_mfma_f32_16x16x32_bf16 v[64:67], v[134:137], v[218:221], 0
	v_mfma_f32_16x16x32_bf16 v[64:67], v[138:141], v[226:229], v[64:67]
	v_mfma_f32_16x16x32_bf16 v[48:51], v[134:137], v[222:225], 0
	v_mfma_f32_16x16x32_bf16 v[48:51], v[138:141], v[230:233], v[48:51]
	v_mfma_f32_16x16x32_bf16 v[32:35], v[134:137], v[234:237], 0
	v_mfma_f32_16x16x32_bf16 v[32:35], v[138:141], v[242:245], v[32:35]
	v_mfma_f32_16x16x32_bf16 v[16:19], v[134:137], v[238:241], 0
	v_mfma_f32_16x16x32_bf16 v[16:19], v[138:141], v[246:249], v[16:19]
	v_mfma_f32_16x16x32_bf16 v[12:15], v[142:145], v[238:241], 0
	v_mfma_f32_16x16x32_bf16 v[12:15], v[146:149], v[246:249], v[12:15]
	v_mfma_f32_16x16x32_bf16 v[28:31], v[142:145], v[234:237], 0
	v_mfma_f32_16x16x32_bf16 v[28:31], v[146:149], v[242:245], v[28:31]
	v_mfma_f32_16x16x32_bf16 v[44:47], v[142:145], v[222:225], 0
	v_mfma_f32_16x16x32_bf16 v[44:47], v[146:149], v[230:233], v[44:47]
	v_mfma_f32_16x16x32_bf16 v[60:63], v[142:145], v[218:221], 0
	v_mfma_f32_16x16x32_bf16 v[60:63], v[146:149], v[226:229], v[60:63]
	v_mfma_f32_16x16x32_bf16 v[56:59], v[150:153], v[218:221], 0
	v_mfma_f32_16x16x32_bf16 v[56:59], v[174:177], v[226:229], v[56:59]
	v_mfma_f32_16x16x32_bf16 v[40:43], v[150:153], v[222:225], 0
	v_mfma_f32_16x16x32_bf16 v[40:43], v[174:177], v[230:233], v[40:43]
	v_mfma_f32_16x16x32_bf16 v[24:27], v[150:153], v[234:237], 0
	v_mfma_f32_16x16x32_bf16 v[24:27], v[174:177], v[242:245], v[24:27]
	v_mfma_f32_16x16x32_bf16 v[8:11], v[150:153], v[238:241], 0
	v_mfma_f32_16x16x32_bf16 v[8:11], v[174:177], v[246:249], v[8:11]
	v_mfma_f32_16x16x32_bf16 v[4:7], v[178:181], v[238:241], 0
	v_mfma_f32_16x16x32_bf16 v[4:7], v[182:185], v[246:249], v[4:7]
	v_mfma_f32_16x16x32_bf16 v[20:23], v[178:181], v[234:237], 0
	v_mfma_f32_16x16x32_bf16 v[20:23], v[182:185], v[242:245], v[20:23]
	v_mfma_f32_16x16x32_bf16 v[36:39], v[178:181], v[222:225], 0
	v_mfma_f32_16x16x32_bf16 v[36:39], v[182:185], v[230:233], v[36:39]
	v_mfma_f32_16x16x32_bf16 v[52:55], v[178:181], v[218:221], 0
	v_mfma_f32_16x16x32_bf16 v[52:55], v[182:185], v[226:229], v[52:55]
	s_barrier
	ds_read_b128 v[134:137], v213
	ds_read_b128 v[138:141], v214
	ds_read_b128 v[142:145], v209
	ds_read_b128 v[146:149], v210
	ds_read_b128 v[150:153], v215
	ds_read_b128 v[174:177], v216
	ds_read_b128 v[178:181], v211
	ds_read_b128 v[182:185], v212
	s_mov_b32 m0, s79
	v_lshl_add_u64 v[250:251], s[82:83], 0, v[0:1]
	ds_read_b128 v[218:221], v207 offset:32768
	ds_read_b128 v[222:225], v207 offset:34816
	ds_read_b128 v[226:229], v208 offset:32768
	ds_read_b128 v[230:233], v208 offset:34816
	ds_read_b128 v[234:237], v207 offset:36864
	ds_read_b128 v[238:241], v207 offset:38912
	ds_read_b128 v[242:245], v208 offset:36864
	ds_read_b128 v[246:249], v208 offset:38912
	global_load_lds_dwordx4 v[250:251], off
	v_lshl_add_u64 v[252:253], v[250:251], 0, s[20:21]
	s_mov_b32 m0, s81
	s_nop 0
	global_load_lds_dwordx4 v[252:253], off
	v_lshl_add_u64 v[252:253], v[250:251], 0, s[14:15]
	s_mov_b32 m0, s97
	v_lshl_add_u64 v[250:251], v[250:251], 0, s[22:23]
	global_load_lds_dwordx4 v[252:253], off
	s_mov_b32 m0, s64
	s_nop 0
	global_load_lds_dwordx4 v[250:251], off
	s_waitcnt vmcnt(8)
	s_waitcnt lgkmcnt(0)
	s_barrier
	v_mfma_f32_16x16x32_bf16 v[128:131], v[134:137], v[218:221], v[128:131]
	v_mfma_f32_16x16x32_bf16 v[128:131], v[138:141], v[226:229], v[128:131]
	v_mfma_f32_16x16x32_bf16 v[112:115], v[138:141], v[230:233], v[112:115]
	v_mfma_f32_16x16x32_bf16 v[112:115], v[134:137], v[222:225], v[112:115]
	v_mfma_f32_16x16x32_bf16 v[96:99], v[134:137], v[234:237], v[96:99]
	v_mfma_f32_16x16x32_bf16 v[96:99], v[138:141], v[242:245], v[96:99]
	v_mfma_f32_16x16x32_bf16 v[80:83], v[138:141], v[246:249], v[80:83]
	v_mfma_f32_16x16x32_bf16 v[80:83], v[134:137], v[238:241], v[80:83]
	v_mfma_f32_16x16x32_bf16 v[76:79], v[142:145], v[238:241], v[76:79]
	v_mfma_f32_16x16x32_bf16 v[76:79], v[146:149], v[246:249], v[76:79]
	v_mfma_f32_16x16x32_bf16 v[92:95], v[146:149], v[242:245], v[92:95]
	v_mfma_f32_16x16x32_bf16 v[92:95], v[142:145], v[234:237], v[92:95]
	v_mfma_f32_16x16x32_bf16 v[108:111], v[142:145], v[222:225], v[108:111]
	v_mfma_f32_16x16x32_bf16 v[108:111], v[146:149], v[230:233], v[108:111]
	v_mfma_f32_16x16x32_bf16 v[124:127], v[146:149], v[226:229], v[124:127]
	v_mfma_f32_16x16x32_bf16 v[124:127], v[142:145], v[218:221], v[124:127]
	v_mfma_f32_16x16x32_bf16 v[120:123], v[150:153], v[218:221], v[120:123]
	v_mfma_f32_16x16x32_bf16 v[120:123], v[174:177], v[226:229], v[120:123]
	v_mfma_f32_16x16x32_bf16 v[104:107], v[174:177], v[230:233], v[104:107]
	v_mfma_f32_16x16x32_bf16 v[104:107], v[150:153], v[222:225], v[104:107]
	v_mfma_f32_16x16x32_bf16 v[88:91], v[150:153], v[234:237], v[88:91]
	v_mfma_f32_16x16x32_bf16 v[88:91], v[174:177], v[242:245], v[88:91]
	v_mfma_f32_16x16x32_bf16 v[72:75], v[174:177], v[246:249], v[72:75]
	v_mfma_f32_16x16x32_bf16 v[72:75], v[150:153], v[238:241], v[72:75]
	v_mfma_f32_16x16x32_bf16 v[68:71], v[178:181], v[238:241], v[68:71]
	v_mfma_f32_16x16x32_bf16 v[68:71], v[182:185], v[246:249], v[68:71]
	v_mfma_f32_16x16x32_bf16 v[84:87], v[182:185], v[242:245], v[84:87]
	v_mfma_f32_16x16x32_bf16 v[84:87], v[178:181], v[234:237], v[84:87]
	v_mfma_f32_16x16x32_bf16 v[100:103], v[178:181], v[222:225], v[100:103]
	v_mfma_f32_16x16x32_bf16 v[100:103], v[182:185], v[230:233], v[100:103]
	v_mfma_f32_16x16x32_bf16 v[116:119], v[182:185], v[226:229], v[116:119]
	v_mfma_f32_16x16x32_bf16 v[116:119], v[178:181], v[218:221], v[116:119]
	s_barrier
	s_add_i32 s24, s70, s77
	v_lshl_add_u64 v[250:251], v[154:155], 0, s[48:49]
	s_mov_b32 m0, s24
	ds_read_b128 v[218:221], v207 offset:49152
	ds_read_b128 v[222:225], v207 offset:51200
	ds_read_b128 v[226:229], v208 offset:49152
	ds_read_b128 v[230:233], v208 offset:51200
	ds_read_b128 v[234:237], v207 offset:53248
	ds_read_b128 v[238:241], v207 offset:55296
	ds_read_b128 v[242:245], v208 offset:53248
	ds_read_b128 v[246:249], v208 offset:55296
	global_load_lds_dwordx4 v[250:251], off
	v_lshl_add_u64 v[250:251], v[154:155], 0, s[50:51]
	s_add_i32 m0, s24, 0x2000
	s_add_i32 s24, s71, s77
	global_load_lds_dwordx4 v[250:251], off
	v_lshl_add_u64 v[250:251], v[154:155], 0, s[52:53]
	s_mov_b32 m0, s24
	v_lshl_add_u64 v[154:155], v[154:155], 0, s[54:55]
	global_load_lds_dwordx4 v[250:251], off
	s_add_i32 m0, s24, 0x2000
	s_nop 0
	global_load_lds_dwordx4 v[154:155], off
	s_waitcnt vmcnt(4)
	s_waitcnt lgkmcnt(0)
	s_barrier
	v_mfma_f32_16x16x32_bf16 v[64:67], v[134:137], v[218:221], v[64:67]
	v_mfma_f32_16x16x32_bf16 v[64:67], v[138:141], v[226:229], v[64:67]
	v_mfma_f32_16x16x32_bf16 v[48:51], v[138:141], v[230:233], v[48:51]
	v_mfma_f32_16x16x32_bf16 v[48:51], v[134:137], v[222:225], v[48:51]
	v_mfma_f32_16x16x32_bf16 v[32:35], v[134:137], v[234:237], v[32:35]
	v_mfma_f32_16x16x32_bf16 v[32:35], v[138:141], v[242:245], v[32:35]
	v_mfma_f32_16x16x32_bf16 v[16:19], v[138:141], v[246:249], v[16:19]
	v_mfma_f32_16x16x32_bf16 v[16:19], v[134:137], v[238:241], v[16:19]
	v_mfma_f32_16x16x32_bf16 v[12:15], v[142:145], v[238:241], v[12:15]
	v_mfma_f32_16x16x32_bf16 v[12:15], v[146:149], v[246:249], v[12:15]
	v_mfma_f32_16x16x32_bf16 v[28:31], v[146:149], v[242:245], v[28:31]
	v_mfma_f32_16x16x32_bf16 v[28:31], v[142:145], v[234:237], v[28:31]
	v_mfma_f32_16x16x32_bf16 v[44:47], v[142:145], v[222:225], v[44:47]
	v_mfma_f32_16x16x32_bf16 v[44:47], v[146:149], v[230:233], v[44:47]
	v_mfma_f32_16x16x32_bf16 v[60:63], v[146:149], v[226:229], v[60:63]
	v_mfma_f32_16x16x32_bf16 v[60:63], v[142:145], v[218:221], v[60:63]
	v_mfma_f32_16x16x32_bf16 v[56:59], v[150:153], v[218:221], v[56:59]
	v_mfma_f32_16x16x32_bf16 v[56:59], v[174:177], v[226:229], v[56:59]
	v_mfma_f32_16x16x32_bf16 v[40:43], v[174:177], v[230:233], v[40:43]
	v_mfma_f32_16x16x32_bf16 v[40:43], v[150:153], v[222:225], v[40:43]
	v_mfma_f32_16x16x32_bf16 v[24:27], v[150:153], v[234:237], v[24:27]
	v_mfma_f32_16x16x32_bf16 v[24:27], v[174:177], v[242:245], v[24:27]
	v_mfma_f32_16x16x32_bf16 v[8:11], v[174:177], v[246:249], v[8:11]
	v_mfma_f32_16x16x32_bf16 v[8:11], v[150:153], v[238:241], v[8:11]
	v_mfma_f32_16x16x32_bf16 v[4:7], v[178:181], v[238:241], v[4:7]
	v_mfma_f32_16x16x32_bf16 v[4:7], v[182:185], v[246:249], v[4:7]
	v_mfma_f32_16x16x32_bf16 v[20:23], v[182:185], v[242:245], v[20:23]
	v_mfma_f32_16x16x32_bf16 v[20:23], v[178:181], v[234:237], v[20:23]
	v_mfma_f32_16x16x32_bf16 v[36:39], v[178:181], v[222:225], v[36:39]
	v_mfma_f32_16x16x32_bf16 v[36:39], v[182:185], v[230:233], v[36:39]
	v_mfma_f32_16x16x32_bf16 v[52:55], v[182:185], v[226:229], v[52:55]
	v_mfma_f32_16x16x32_bf16 v[52:55], v[178:181], v[218:221], v[52:55]
	s_barrier
	s_add_i32 s94, s94, 2
	s_add_u32 vcc_lo, vcc_lo, 0x100
	s_addc_u32 vcc_hi, vcc_hi, 0
	s_cmp_gt_u32 s94, 13

.LBB0_387:
	s_lshl_b32 s29, s80, 8
	s_add_i32 s29, s29, s65
	v_or_b32_e32 v174, s29, v3
	s_cmp_gt_i32 s96, 13
	s_mov_b64 s[4:5], -1
	s_cbranch_scc0 .LBB0_390
	v_lshl_add_u32 v160, s96, 7, v198
	v_and_b32_e32 v140, 0xff, v198
	v_lshlrev_b32_e32 v140, 2, v140
	v_add_u32_e32 v140, 0x27500, v140
	ds_read_b128 v[136:139], v140 offset:16
	ds_read_b128 v[144:147], v140
	ds_read_b128 v[132:135], v140 offset:528
	ds_read_b128 v[140:143], v140 offset:512
	v_ashrrev_i32_e32 v175, 31, v174
	v_lshlrev_b64 v[148:149], 10, v[174:175]
	v_lshl_add_u64 v[148:149], v[148:149], 0, v[160:161]
	v_lshlrev_b64 v[148:149], 1, v[148:149]
	s_mov_b64 s[4:5], 0x48000
	s_waitcnt lgkmcnt(0)
	v_add_f32_e32 v150, v128, v144
	v_mul_f32_e32 v150, 0xbfb8aa3b, v150
	v_exp_f32_e32 v150, v150
	v_add_f32_e32 v176, v123, v143
	v_mul_f32_e32 v176, 0xbfb8aa3b, v176
	v_exp_f32_e32 v176, v176
	v_add_f32_e32 v151, 1.0, v150
	v_add_f32_e32 v150, v120, v140
	v_mul_f32_e32 v150, 0xbfb8aa3b, v150
	v_exp_f32_e32 v150, v150
	v_rcp_f32_e32 v151, v151
	v_add_f32_e32 v176, 1.0, v176
	v_rcp_f32_e32 v182, v176
	v_add_f32_e32 v152, 1.0, v150
	v_rcp_f32_e32 v150, v152
	v_mul_f32_e32 v151, v152, v151
	v_add_f32_e32 v152, v129, v145
	v_mul_f32_e32 v152, 0xbfb8aa3b, v152
	v_exp_f32_e32 v152, v152
	v_add_f32_e32 v177, v116, v132
	v_mul_f32_e32 v177, 0xbfb8aa3b, v177
	v_exp_f32_e32 v177, v177
	v_add_f32_e32 v153, 1.0, v152
	v_add_f32_e32 v152, v121, v141
	v_mul_f32_e32 v152, 0xbfb8aa3b, v152
	v_exp_f32_e32 v152, v152
	v_rcp_f32_e32 v153, v153
	v_add_f32_e32 v177, 1.0, v177
	v_rcp_f32_e32 v183, v177
	v_add_f32_e32 v154, 1.0, v152
	v_rcp_f32_e32 v152, v154
	v_mul_f32_e32 v153, v154, v153
	v_add_f32_e32 v154, v130, v146
	v_mul_f32_e32 v154, 0xbfb8aa3b, v154
	v_exp_f32_e32 v154, v154
	s_nop 0
	v_add_f32_e32 v155, 1.0, v154
	v_add_f32_e32 v154, v122, v142
	v_mul_f32_e32 v154, 0xbfb8aa3b, v154
	v_exp_f32_e32 v154, v154
	v_rcp_f32_e32 v155, v155
	v_add_f32_e32 v175, 1.0, v154
	v_rcp_f32_e32 v154, v175
	v_mul_f32_e32 v155, v175, v155
	v_add_f32_e32 v175, v131, v147
	v_mul_f32_e32 v175, 0xbfb8aa3b, v175
	v_exp_f32_e32 v175, v175
	s_nop 0
	v_add_f32_e32 v175, 1.0, v175
	v_rcp_f32_e32 v175, v175
	s_nop 0
	v_mul_f32_e32 v175, v176, v175
	v_add_f32_e32 v176, v124, v136
	v_mul_f32_e32 v176, 0xbfb8aa3b, v176
	v_exp_f32_e32 v176, v176
	s_nop 0
	v_add_f32_e32 v176, 1.0, v176
	v_rcp_f32_e32 v176, v176
	s_nop 0
	v_mul_f32_e32 v178, v177, v176
	v_add_f32_e32 v176, v125, v137
	v_mul_f32_e32 v176, 0xbfb8aa3b, v176
	v_exp_f32_e32 v176, v176
	v_add_f32_e32 v177, v117, v133
	v_mul_f32_e32 v177, 0xbfb8aa3b, v177
	v_exp_f32_e32 v177, v177
	v_add_f32_e32 v176, 1.0, v176
	v_rcp_f32_e32 v176, v176
	v_add_f32_e32 v177, 1.0, v177
	v_rcp_f32_e32 v184, v177
	v_mul_f32_e32 v179, v177, v176
	v_add_f32_e32 v176, v126, v138
	v_mul_f32_e32 v176, 0xbfb8aa3b, v176
	v_exp_f32_e32 v176, v176
	v_add_f32_e32 v177, v118, v134
	v_mul_f32_e32 v177, 0xbfb8aa3b, v177
	v_exp_f32_e32 v177, v177
	v_add_f32_e32 v176, 1.0, v176
	v_rcp_f32_e32 v176, v176
	v_add_f32_e32 v177, 1.0, v177
	v_rcp_f32_e32 v185, v177
	v_mul_f32_e32 v180, v177, v176
	v_add_f32_e32 v176, v127, v139
	v_mul_f32_e32 v176, 0xbfb8aa3b, v176
	v_exp_f32_e32 v176, v176
	v_add_f32_e32 v177, v119, v135
	v_mul_f32_e32 v177, 0xbfb8aa3b, v177
	v_exp_f32_e32 v177, v177
	v_add_f32_e32 v176, 1.0, v176
	v_rcp_f32_e32 v176, v176
	v_add_f32_e32 v177, 1.0, v177
	v_rcp_f32_e32 v217, v177
	v_mul_f32_e32 v181, v177, v176
	v_cvt_pk_bf16_f32 v176, v151, v153
	v_cvt_pk_bf16_f32 v177, v155, v175
	v_cvt_pk_bf16_f32 v178, v178, v179
	v_cvt_pk_bf16_f32 v179, v180, v181
	v_lshl_add_u64 v[180:181], s[44:45], 0, v[148:149]
	global_store_dwordx4 v[180:181], v[176:179], off
	v_cvt_pk_bf16_f32 v150, v150, v152
	v_cvt_pk_bf16_f32 v151, v154, v182
	v_cvt_pk_bf16_f32 v152, v183, v184
	v_lshl_add_u64 v[154:155], s[46:47], 0, v[148:149]
	v_cvt_pk_bf16_f32 v153, v185, v217
	global_store_dwordx4 v[154:155], v[150:153], off
	v_add_f32_e32 v154, v105, v141
	v_mul_f32_e32 v154, 0xbfb8aa3b, v154
	v_add_f32_e32 v152, v112, v144
	v_mul_f32_e32 v152, 0xbfb8aa3b, v152
	v_exp_f32_e32 v152, v152
	v_add_f32_e32 v153, v104, v140
	v_mul_f32_e32 v153, 0xbfb8aa3b, v153
	v_exp_f32_e32 v153, v153
	v_add_f32_e32 v152, 1.0, v152
	v_rcp_f32_e32 v152, v152
	v_exp_f32_e32 v154, v154
	v_add_f32_e32 v153, 1.0, v153
	v_rcp_f32_e32 v175, v153
	v_mul_f32_e32 v152, v153, v152
	v_add_f32_e32 v153, v113, v145
	v_mul_f32_e32 v153, 0xbfb8aa3b, v153
	v_exp_f32_e32 v153, v153
	v_add_f32_e32 v154, 1.0, v154
	v_rcp_f32_e32 v178, v154
	v_add_f32_e32 v155, v106, v142
	v_add_f32_e32 v153, 1.0, v153
	v_rcp_f32_e32 v153, v153
	v_mul_f32_e32 v155, 0xbfb8aa3b, v155
	v_exp_f32_e32 v155, v155
	v_or_b32_e32 v150, 16, v174
	v_mul_f32_e32 v153, v154, v153
	v_add_f32_e32 v154, v114, v146
	v_mul_f32_e32 v154, 0xbfb8aa3b, v154
	v_exp_f32_e32 v154, v154
	v_add_f32_e32 v155, 1.0, v155
	v_rcp_f32_e32 v179, v155
	v_ashrrev_i32_e32 v151, 31, v150
	v_add_f32_e32 v154, 1.0, v154
	v_rcp_f32_e32 v154, v154
	v_lshlrev_b64 v[150:151], 10, v[150:151]
	v_mul_f32_e32 v176, v155, v154
	v_add_f32_e32 v154, v115, v147
	v_mul_f32_e32 v154, 0xbfb8aa3b, v154
	v_exp_f32_e32 v154, v154
	v_add_f32_e32 v155, v107, v143
	v_mul_f32_e32 v155, 0xbfb8aa3b, v155
	v_exp_f32_e32 v155, v155
	v_add_f32_e32 v154, 1.0, v154
	v_rcp_f32_e32 v154, v154
	v_add_f32_e32 v155, 1.0, v155
	v_rcp_f32_e32 v180, v155
	v_mul_f32_e32 v177, v155, v154
	v_add_f32_e32 v154, v108, v136
	v_mul_f32_e32 v154, 0xbfb8aa3b, v154
	v_exp_f32_e32 v154, v154
	v_add_f32_e32 v155, v100, v132
	v_mul_f32_e32 v155, 0xbfb8aa3b, v155
	v_exp_f32_e32 v155, v155
	v_add_f32_e32 v154, 1.0, v154
	v_rcp_f32_e32 v154, v154
	v_add_f32_e32 v155, 1.0, v155
	v_rcp_f32_e32 v181, v155
	v_mul_f32_e32 v182, v155, v154
	v_add_f32_e32 v154, v109, v137
	v_mul_f32_e32 v154, 0xbfb8aa3b, v154
	v_exp_f32_e32 v154, v154
	v_add_f32_e32 v155, v101, v133
	v_mul_f32_e32 v155, 0xbfb8aa3b, v155
	v_exp_f32_e32 v155, v155
	v_add_f32_e32 v154, 1.0, v154
	v_rcp_f32_e32 v154, v154
	v_add_f32_e32 v155, 1.0, v155
	v_rcp_f32_e32 v183, v155
	v_mul_f32_e32 v184, v155, v154
	v_add_f32_e32 v154, v110, v138
	v_mul_f32_e32 v154, 0xbfb8aa3b, v154
	v_exp_f32_e32 v154, v154
	v_add_f32_e32 v155, v102, v134
	v_mul_f32_e32 v155, 0xbfb8aa3b, v155
	v_exp_f32_e32 v155, v155
	v_add_f32_e32 v154, 1.0, v154
	v_rcp_f32_e32 v154, v154
	v_add_f32_e32 v155, 1.0, v155
	v_rcp_f32_e32 v185, v155
	v_mul_f32_e32 v217, v155, v154
	v_add_f32_e32 v154, v111, v139
	v_mul_f32_e32 v154, 0xbfb8aa3b, v154
	v_exp_f32_e32 v154, v154
	v_add_f32_e32 v155, v103, v135
	v_mul_f32_e32 v155, 0xbfb8aa3b, v155
	v_exp_f32_e32 v155, v155
	v_add_f32_e32 v154, 1.0, v154
	v_rcp_f32_e32 v154, v154
	v_add_f32_e32 v155, 1.0, v155
	v_rcp_f32_e32 v218, v155
	v_mul_f32_e32 v219, v155, v154
	v_lshl_add_u64 v[154:155], v[150:151], 0, v[160:161]
	v_lshlrev_b64 v[154:155], 1, v[154:155]
	v_cvt_pk_bf16_f32 v150, v152, v153
	v_cvt_pk_bf16_f32 v151, v176, v177
	v_cvt_pk_bf16_f32 v152, v182, v184
	v_lshl_add_u64 v[176:177], s[44:45], 0, v[154:155]
	v_cvt_pk_bf16_f32 v153, v217, v219
	global_store_dwordx4 v[176:177], v[150:153], off
	v_lshl_add_u64 v[154:155], s[46:47], 0, v[154:155]
	s_nop 0
	v_cvt_pk_bf16_f32 v150, v175, v178
	v_cvt_pk_bf16_f32 v151, v179, v180
	v_cvt_pk_bf16_f32 v152, v181, v183
	v_cvt_pk_bf16_f32 v153, v185, v218
	global_store_dwordx4 v[154:155], v[150:153], off
	v_add_f32_e32 v154, v89, v141
	v_mul_f32_e32 v154, 0xbfb8aa3b, v154
	v_add_f32_e32 v152, v96, v144
	v_mul_f32_e32 v152, 0xbfb8aa3b, v152
	v_exp_f32_e32 v152, v152
	v_add_f32_e32 v153, v88, v140
	v_mul_f32_e32 v153, 0xbfb8aa3b, v153
	v_exp_f32_e32 v153, v153
	v_add_f32_e32 v152, 1.0, v152
	v_rcp_f32_e32 v152, v152
	v_exp_f32_e32 v154, v154
	v_add_f32_e32 v153, 1.0, v153
	v_rcp_f32_e32 v175, v153
	v_mul_f32_e32 v152, v153, v152
	v_add_f32_e32 v153, v97, v145
	v_mul_f32_e32 v153, 0xbfb8aa3b, v153
	v_exp_f32_e32 v153, v153
	v_add_f32_e32 v154, 1.0, v154
	v_rcp_f32_e32 v178, v154
	v_add_f32_e32 v155, v90, v142
	v_add_f32_e32 v153, 1.0, v153
	v_rcp_f32_e32 v153, v153
	v_mul_f32_e32 v155, 0xbfb8aa3b, v155
	v_exp_f32_e32 v155, v155
	v_or_b32_e32 v150, 32, v174
	v_mul_f32_e32 v153, v154, v153
	v_add_f32_e32 v154, v98, v146
	v_mul_f32_e32 v154, 0xbfb8aa3b, v154
	v_exp_f32_e32 v154, v154
	v_add_f32_e32 v155, 1.0, v155
	v_rcp_f32_e32 v179, v155
	v_ashrrev_i32_e32 v151, 31, v150
	v_add_f32_e32 v154, 1.0, v154
	v_rcp_f32_e32 v154, v154
	v_lshlrev_b64 v[150:151], 10, v[150:151]
	v_mul_f32_e32 v176, v155, v154
	v_add_f32_e32 v154, v99, v147
	v_mul_f32_e32 v154, 0xbfb8aa3b, v154
	v_exp_f32_e32 v154, v154
	v_add_f32_e32 v155, v91, v143
	v_mul_f32_e32 v155, 0xbfb8aa3b, v155
	v_exp_f32_e32 v155, v155
	v_add_f32_e32 v154, 1.0, v154
	v_rcp_f32_e32 v154, v154
	v_add_f32_e32 v155, 1.0, v155
	v_rcp_f32_e32 v180, v155
	v_mul_f32_e32 v177, v155, v154
	v_add_f32_e32 v154, v92, v136
	v_mul_f32_e32 v154, 0xbfb8aa3b, v154
	v_exp_f32_e32 v154, v154
	v_add_f32_e32 v155, v84, v132
	v_mul_f32_e32 v155, 0xbfb8aa3b, v155
	v_exp_f32_e32 v155, v155
	v_add_f32_e32 v154, 1.0, v154
	v_rcp_f32_e32 v154, v154
	v_add_f32_e32 v155, 1.0, v155
	v_rcp_f32_e32 v181, v155
	v_mul_f32_e32 v182, v155, v154
	v_add_f32_e32 v154, v93, v137
	v_mul_f32_e32 v154, 0xbfb8aa3b, v154
	v_exp_f32_e32 v154, v154
	v_add_f32_e32 v155, v85, v133
	v_mul_f32_e32 v155, 0xbfb8aa3b, v155
	v_exp_f32_e32 v155, v155
	v_add_f32_e32 v154, 1.0, v154
	v_rcp_f32_e32 v154, v154
	v_add_f32_e32 v155, 1.0, v155
	v_rcp_f32_e32 v183, v155
	v_mul_f32_e32 v184, v155, v154
	v_add_f32_e32 v154, v94, v138
	v_mul_f32_e32 v154, 0xbfb8aa3b, v154
	v_exp_f32_e32 v154, v154
	v_add_f32_e32 v155, v86, v134
	v_mul_f32_e32 v155, 0xbfb8aa3b, v155
	v_exp_f32_e32 v155, v155
	v_add_f32_e32 v154, 1.0, v154
	v_rcp_f32_e32 v154, v154
	v_add_f32_e32 v155, 1.0, v155
	v_rcp_f32_e32 v185, v155
	v_mul_f32_e32 v217, v155, v154
	v_add_f32_e32 v154, v95, v139
	v_mul_f32_e32 v154, 0xbfb8aa3b, v154
	v_exp_f32_e32 v154, v154
	v_add_f32_e32 v155, v87, v135
	v_mul_f32_e32 v155, 0xbfb8aa3b, v155
	v_exp_f32_e32 v155, v155
	v_add_f32_e32 v154, 1.0, v154
	v_rcp_f32_e32 v154, v154
	v_add_f32_e32 v155, 1.0, v155
	v_rcp_f32_e32 v218, v155
	v_mul_f32_e32 v219, v155, v154
	v_lshl_add_u64 v[154:155], v[150:151], 0, v[160:161]
	v_lshlrev_b64 v[154:155], 1, v[154:155]
	v_cvt_pk_bf16_f32 v150, v152, v153
	v_cvt_pk_bf16_f32 v151, v176, v177
	v_cvt_pk_bf16_f32 v152, v182, v184
	v_lshl_add_u64 v[176:177], s[44:45], 0, v[154:155]
	v_cvt_pk_bf16_f32 v153, v217, v219
	global_store_dwordx4 v[176:177], v[150:153], off
	v_lshl_add_u64 v[154:155], s[46:47], 0, v[154:155]
	s_nop 0
	v_cvt_pk_bf16_f32 v150, v175, v178
	v_cvt_pk_bf16_f32 v151, v179, v180
	v_cvt_pk_bf16_f32 v152, v181, v183
	v_cvt_pk_bf16_f32 v153, v185, v218
	global_store_dwordx4 v[154:155], v[150:153], off
	v_add_f32_e32 v154, v73, v141
	v_mul_f32_e32 v154, 0xbfb8aa3b, v154
	v_add_f32_e32 v152, v80, v144
	v_mul_f32_e32 v152, 0xbfb8aa3b, v152
	v_exp_f32_e32 v152, v152
	v_add_f32_e32 v153, v72, v140
	v_mul_f32_e32 v153, 0xbfb8aa3b, v153
	v_exp_f32_e32 v153, v153
	v_add_f32_e32 v152, 1.0, v152
	v_rcp_f32_e32 v152, v152
	v_exp_f32_e32 v154, v154
	v_add_f32_e32 v153, 1.0, v153
	v_rcp_f32_e32 v175, v153
	v_mul_f32_e32 v152, v153, v152
	v_add_f32_e32 v153, v81, v145
	v_mul_f32_e32 v153, 0xbfb8aa3b, v153
	v_exp_f32_e32 v153, v153
	v_add_f32_e32 v154, 1.0, v154
	v_rcp_f32_e32 v178, v154
	v_add_f32_e32 v155, v74, v142
	v_add_f32_e32 v153, 1.0, v153
	v_rcp_f32_e32 v153, v153
	v_mul_f32_e32 v155, 0xbfb8aa3b, v155
	v_exp_f32_e32 v155, v155
	v_or_b32_e32 v150, 48, v174
	v_mul_f32_e32 v153, v154, v153
	v_add_f32_e32 v154, v82, v146
	v_mul_f32_e32 v154, 0xbfb8aa3b, v154
	v_exp_f32_e32 v154, v154
	v_add_f32_e32 v155, 1.0, v155
	v_rcp_f32_e32 v179, v155
	v_ashrrev_i32_e32 v151, 31, v150
	v_add_f32_e32 v154, 1.0, v154
	v_rcp_f32_e32 v154, v154
	v_lshlrev_b64 v[150:151], 10, v[150:151]
	v_mul_f32_e32 v176, v155, v154
	v_add_f32_e32 v154, v83, v147
	v_mul_f32_e32 v154, 0xbfb8aa3b, v154
	v_exp_f32_e32 v154, v154
	v_add_f32_e32 v155, v75, v143
	v_mul_f32_e32 v155, 0xbfb8aa3b, v155
	v_exp_f32_e32 v155, v155
	v_add_f32_e32 v154, 1.0, v154
	v_rcp_f32_e32 v154, v154
	v_add_f32_e32 v155, 1.0, v155
	v_rcp_f32_e32 v180, v155
	v_mul_f32_e32 v177, v155, v154
	v_add_f32_e32 v154, v76, v136
	v_mul_f32_e32 v154, 0xbfb8aa3b, v154
	v_exp_f32_e32 v154, v154
	v_add_f32_e32 v155, v68, v132
	v_mul_f32_e32 v155, 0xbfb8aa3b, v155
	v_exp_f32_e32 v155, v155
	v_add_f32_e32 v154, 1.0, v154
	v_rcp_f32_e32 v154, v154
	v_add_f32_e32 v155, 1.0, v155
	v_rcp_f32_e32 v181, v155
	v_mul_f32_e32 v182, v155, v154
	v_add_f32_e32 v154, v77, v137
	v_mul_f32_e32 v154, 0xbfb8aa3b, v154
	v_exp_f32_e32 v154, v154
	v_add_f32_e32 v155, v69, v133
	v_mul_f32_e32 v155, 0xbfb8aa3b, v155
	v_exp_f32_e32 v155, v155
	v_add_f32_e32 v154, 1.0, v154
	v_rcp_f32_e32 v154, v154
	v_add_f32_e32 v155, 1.0, v155
	v_rcp_f32_e32 v183, v155
	v_mul_f32_e32 v184, v155, v154
	v_add_f32_e32 v154, v78, v138
	v_mul_f32_e32 v154, 0xbfb8aa3b, v154
	v_exp_f32_e32 v154, v154
	v_add_f32_e32 v155, v70, v134
	v_mul_f32_e32 v155, 0xbfb8aa3b, v155
	v_exp_f32_e32 v155, v155
	v_add_f32_e32 v154, 1.0, v154
	v_rcp_f32_e32 v154, v154
	v_add_f32_e32 v155, 1.0, v155
	v_rcp_f32_e32 v185, v155
	v_mul_f32_e32 v217, v155, v154
	v_add_f32_e32 v154, v79, v139
	v_mul_f32_e32 v154, 0xbfb8aa3b, v154
	v_exp_f32_e32 v154, v154
	v_add_f32_e32 v155, v71, v135
	v_mul_f32_e32 v155, 0xbfb8aa3b, v155
	v_exp_f32_e32 v155, v155
	v_add_f32_e32 v154, 1.0, v154
	v_rcp_f32_e32 v154, v154
	v_add_f32_e32 v155, 1.0, v155
	v_rcp_f32_e32 v218, v155
	v_mul_f32_e32 v219, v155, v154
	v_lshl_add_u64 v[154:155], v[150:151], 0, v[160:161]
	v_lshlrev_b64 v[154:155], 1, v[154:155]
	v_cvt_pk_bf16_f32 v150, v152, v153
	v_cvt_pk_bf16_f32 v151, v176, v177
	v_lshl_add_u64 v[176:177], s[44:45], 0, v[154:155]
	v_cvt_pk_bf16_f32 v152, v182, v184
	v_cvt_pk_bf16_f32 v153, v217, v219
	global_store_dwordx4 v[176:177], v[150:153], off
	v_lshl_add_u64 v[154:155], s[46:47], 0, v[154:155]
	v_add_f32_e32 v176, v53, v133
	v_cvt_pk_bf16_f32 v150, v175, v178
	v_cvt_pk_bf16_f32 v151, v179, v180
	v_cvt_pk_bf16_f32 v152, v181, v183
	v_cvt_pk_bf16_f32 v153, v185, v218
	global_store_dwordx4 v[154:155], v[150:153], off
	v_add_f32_e32 v154, v59, v143
	v_mul_f32_e32 v154, 0xbfb8aa3b, v154
	v_add_f32_e32 v150, v64, v144
	v_mul_f32_e32 v150, 0xbfb8aa3b, v150
	v_exp_f32_e32 v150, v150
	v_add_f32_e32 v151, v56, v140
	v_mul_f32_e32 v151, 0xbfb8aa3b, v151
	v_exp_f32_e32 v151, v151
	v_add_f32_e32 v150, 1.0, v150
	v_rcp_f32_e32 v150, v150
	v_add_f32_e32 v152, v57, v141
	v_add_f32_e32 v151, 1.0, v151
	v_rcp_f32_e32 v160, v151
	v_mul_f32_e32 v150, v151, v150
	v_add_f32_e32 v151, v65, v145
	v_mul_f32_e32 v151, 0xbfb8aa3b, v151
	v_exp_f32_e32 v151, v151
	v_mul_f32_e32 v152, 0xbfb8aa3b, v152
	v_exp_f32_e32 v152, v152
	v_add_f32_e32 v153, v58, v142
	v_add_f32_e32 v151, 1.0, v151
	v_rcp_f32_e32 v151, v151
	v_add_f32_e32 v152, 1.0, v152
	v_rcp_f32_e32 v175, v152
	v_mul_f32_e32 v153, 0xbfb8aa3b, v153
	v_mul_f32_e32 v151, v152, v151
	v_add_f32_e32 v152, v66, v146
	v_mul_f32_e32 v152, 0xbfb8aa3b, v152
	v_exp_f32_e32 v152, v152
	v_exp_f32_e32 v153, v153
	v_exp_f32_e32 v154, v154
	v_add_f32_e32 v155, v52, v132
	v_add_f32_e32 v152, 1.0, v152
	v_rcp_f32_e32 v152, v152
	v_add_f32_e32 v153, 1.0, v153
	v_rcp_f32_e32 v178, v153
	v_add_f32_e32 v154, 1.0, v154
	v_mul_f32_e32 v152, v153, v152
	v_add_f32_e32 v153, v67, v147
	v_mul_f32_e32 v153, 0xbfb8aa3b, v153
	v_exp_f32_e32 v153, v153
	v_rcp_f32_e32 v179, v154
	v_mul_f32_e32 v155, 0xbfb8aa3b, v155
	v_exp_f32_e32 v155, v155
	v_add_f32_e32 v153, 1.0, v153
	v_rcp_f32_e32 v153, v153
	v_mul_f32_e32 v176, 0xbfb8aa3b, v176
	v_add_f32_e32 v155, 1.0, v155
	v_rcp_f32_e32 v180, v155
	v_mul_f32_e32 v153, v154, v153
	v_add_f32_e32 v154, v60, v136
	v_mul_f32_e32 v154, 0xbfb8aa3b, v154
	v_exp_f32_e32 v154, v154
	v_exp_f32_e32 v176, v176
	v_add_f32_e32 v177, v54, v134
	v_mul_f32_e32 v177, 0xbfb8aa3b, v177
	v_add_f32_e32 v154, 1.0, v154
	v_rcp_f32_e32 v154, v154
	v_add_f32_e32 v176, 1.0, v176
	v_rcp_f32_e32 v181, v176
	v_exp_f32_e32 v177, v177
	v_mul_f32_e32 v154, v155, v154
	v_add_f32_e32 v155, v61, v137
	v_mul_f32_e32 v155, 0xbfb8aa3b, v155
	v_exp_f32_e32 v155, v155
	v_add_f32_e32 v177, 1.0, v177
	v_rcp_f32_e32 v182, v177
	v_add_f32_e32 v183, v55, v135
	v_add_f32_e32 v155, 1.0, v155
	v_rcp_f32_e32 v155, v155
	v_mul_f32_e32 v183, 0xbfb8aa3b, v183
	v_exp_f32_e32 v183, v183
	v_cvt_pk_bf16_f32 v150, v150, v151
	v_mul_f32_e32 v155, v176, v155
	v_add_f32_e32 v176, v62, v138
	v_mul_f32_e32 v176, 0xbfb8aa3b, v176
	v_exp_f32_e32 v176, v176
	v_add_f32_e32 v183, 1.0, v183
	v_cvt_pk_bf16_f32 v151, v152, v153
	v_cvt_pk_bf16_f32 v152, v154, v155
	v_add_f32_e32 v176, 1.0, v176
	v_rcp_f32_e32 v176, v176
	v_lshl_add_u64 v[154:155], v[148:149], 0, s[14:15]
	v_rcp_f32_e32 v184, v183
	v_mul_f32_e32 v176, v177, v176
	v_add_f32_e32 v177, v63, v139
	v_mul_f32_e32 v177, 0xbfb8aa3b, v177
	v_exp_f32_e32 v177, v177
	s_nop 0
	v_add_f32_e32 v177, 1.0, v177
	v_rcp_f32_e32 v177, v177
	s_nop 0
	v_mul_f32_e32 v177, v183, v177
	v_cvt_pk_bf16_f32 v153, v176, v177
	v_lshl_add_u64 v[176:177], s[44:45], 0, v[154:155]
	global_store_dwordx4 v[176:177], v[150:153], off
	v_lshl_add_u64 v[154:155], s[46:47], 0, v[154:155]
	v_add_f32_e32 v176, v37, v133
	v_cvt_pk_bf16_f32 v150, v160, v175
	v_cvt_pk_bf16_f32 v151, v178, v179
	v_cvt_pk_bf16_f32 v152, v180, v181
	v_cvt_pk_bf16_f32 v153, v182, v184
	global_store_dwordx4 v[154:155], v[150:153], off
	v_add_f32_e32 v154, v43, v143
	v_mul_f32_e32 v154, 0xbfb8aa3b, v154
	v_add_f32_e32 v150, v48, v144
	v_mul_f32_e32 v150, 0xbfb8aa3b, v150
	v_exp_f32_e32 v150, v150
	v_add_f32_e32 v151, v40, v140
	v_mul_f32_e32 v151, 0xbfb8aa3b, v151
	v_exp_f32_e32 v151, v151
	v_add_f32_e32 v150, 1.0, v150
	v_rcp_f32_e32 v150, v150
	v_add_f32_e32 v152, v41, v141
	v_add_f32_e32 v151, 1.0, v151
	v_rcp_f32_e32 v160, v151
	v_mul_f32_e32 v150, v151, v150
	v_add_f32_e32 v151, v49, v145
	v_mul_f32_e32 v151, 0xbfb8aa3b, v151
	v_exp_f32_e32 v151, v151
	v_mul_f32_e32 v152, 0xbfb8aa3b, v152
	v_exp_f32_e32 v152, v152
	v_add_f32_e32 v153, v42, v142
	v_add_f32_e32 v151, 1.0, v151
	v_rcp_f32_e32 v151, v151
	v_add_f32_e32 v152, 1.0, v152
	v_rcp_f32_e32 v175, v152
	v_mul_f32_e32 v153, 0xbfb8aa3b, v153
	v_mul_f32_e32 v151, v152, v151
	v_add_f32_e32 v152, v50, v146
	v_mul_f32_e32 v152, 0xbfb8aa3b, v152
	v_exp_f32_e32 v152, v152
	v_exp_f32_e32 v153, v153
	v_exp_f32_e32 v154, v154
	v_add_f32_e32 v155, v36, v132
	v_add_f32_e32 v152, 1.0, v152
	v_rcp_f32_e32 v152, v152
	v_add_f32_e32 v153, 1.0, v153
	v_rcp_f32_e32 v178, v153
	v_add_f32_e32 v154, 1.0, v154
	v_mul_f32_e32 v152, v153, v152
	v_add_f32_e32 v153, v51, v147
	v_mul_f32_e32 v153, 0xbfb8aa3b, v153
	v_exp_f32_e32 v153, v153
	v_rcp_f32_e32 v179, v154
	v_mul_f32_e32 v155, 0xbfb8aa3b, v155
	v_exp_f32_e32 v155, v155
	v_add_f32_e32 v153, 1.0, v153
	v_rcp_f32_e32 v153, v153
	v_mul_f32_e32 v176, 0xbfb8aa3b, v176
	v_add_f32_e32 v155, 1.0, v155
	v_rcp_f32_e32 v180, v155
	v_mul_f32_e32 v153, v154, v153
	v_add_f32_e32 v154, v44, v136
	v_mul_f32_e32 v154, 0xbfb8aa3b, v154
	v_exp_f32_e32 v154, v154
	v_exp_f32_e32 v176, v176
	v_add_f32_e32 v177, v38, v134
	v_mul_f32_e32 v177, 0xbfb8aa3b, v177
	v_add_f32_e32 v154, 1.0, v154
	v_rcp_f32_e32 v154, v154
	v_add_f32_e32 v176, 1.0, v176
	v_rcp_f32_e32 v181, v176
	v_exp_f32_e32 v177, v177
	v_mul_f32_e32 v154, v155, v154
	v_add_f32_e32 v155, v45, v137
	v_mul_f32_e32 v155, 0xbfb8aa3b, v155
	v_exp_f32_e32 v155, v155
	v_add_f32_e32 v177, 1.0, v177
	v_rcp_f32_e32 v182, v177
	v_add_f32_e32 v183, v39, v135
	v_add_f32_e32 v155, 1.0, v155
	v_rcp_f32_e32 v155, v155
	v_mul_f32_e32 v183, 0xbfb8aa3b, v183
	v_exp_f32_e32 v183, v183
	v_cvt_pk_bf16_f32 v150, v150, v151
	v_mul_f32_e32 v155, v176, v155
	v_add_f32_e32 v176, v46, v138
	v_mul_f32_e32 v176, 0xbfb8aa3b, v176
	v_exp_f32_e32 v176, v176
	v_add_f32_e32 v183, 1.0, v183
	v_cvt_pk_bf16_f32 v151, v152, v153
	v_cvt_pk_bf16_f32 v152, v154, v155
	v_add_f32_e32 v176, 1.0, v176
	v_rcp_f32_e32 v176, v176
	v_lshl_add_u64 v[154:155], v[148:149], 0, s[4:5]
	v_rcp_f32_e32 v184, v183
	s_mov_b64 s[4:5], 0x58000
	v_mul_f32_e32 v176, v177, v176
	v_add_f32_e32 v177, v47, v139
	v_mul_f32_e32 v177, 0xbfb8aa3b, v177
	v_exp_f32_e32 v177, v177
	s_nop 0
	v_add_f32_e32 v177, 1.0, v177
	v_rcp_f32_e32 v177, v177
	s_nop 0
	v_mul_f32_e32 v177, v183, v177
	v_cvt_pk_bf16_f32 v153, v176, v177
	v_lshl_add_u64 v[176:177], s[44:45], 0, v[154:155]
	global_store_dwordx4 v[176:177], v[150:153], off
	v_lshl_add_u64 v[154:155], s[46:47], 0, v[154:155]
	v_add_f32_e32 v176, v21, v133
	v_cvt_pk_bf16_f32 v150, v160, v175
	v_cvt_pk_bf16_f32 v151, v178, v179
	v_cvt_pk_bf16_f32 v152, v180, v181
	v_cvt_pk_bf16_f32 v153, v182, v184
	global_store_dwordx4 v[154:155], v[150:153], off
	v_add_f32_e32 v154, v27, v143
	v_mul_f32_e32 v154, 0xbfb8aa3b, v154
	v_add_f32_e32 v150, v32, v144
	v_mul_f32_e32 v150, 0xbfb8aa3b, v150
	v_exp_f32_e32 v150, v150
	v_add_f32_e32 v151, v24, v140
	v_mul_f32_e32 v151, 0xbfb8aa3b, v151
	v_exp_f32_e32 v151, v151
	v_add_f32_e32 v150, 1.0, v150
	v_rcp_f32_e32 v150, v150
	v_add_f32_e32 v152, v25, v141
	v_add_f32_e32 v151, 1.0, v151
	v_rcp_f32_e32 v160, v151
	v_mul_f32_e32 v150, v151, v150
	v_add_f32_e32 v151, v33, v145
	v_mul_f32_e32 v151, 0xbfb8aa3b, v151
	v_exp_f32_e32 v151, v151
	v_mul_f32_e32 v152, 0xbfb8aa3b, v152
	v_exp_f32_e32 v152, v152
	v_add_f32_e32 v153, v26, v142
	v_add_f32_e32 v151, 1.0, v151
	v_rcp_f32_e32 v151, v151
	v_add_f32_e32 v152, 1.0, v152
	v_rcp_f32_e32 v175, v152
	v_mul_f32_e32 v153, 0xbfb8aa3b, v153
	v_mul_f32_e32 v151, v152, v151
	v_add_f32_e32 v152, v34, v146
	v_mul_f32_e32 v152, 0xbfb8aa3b, v152
	v_exp_f32_e32 v152, v152
	v_exp_f32_e32 v153, v153
	v_exp_f32_e32 v154, v154
	v_add_f32_e32 v155, v20, v132
	v_add_f32_e32 v152, 1.0, v152
	v_rcp_f32_e32 v152, v152
	v_add_f32_e32 v153, 1.0, v153
	v_rcp_f32_e32 v178, v153
	v_add_f32_e32 v154, 1.0, v154
	v_mul_f32_e32 v152, v153, v152
	v_add_f32_e32 v153, v35, v147
	v_mul_f32_e32 v153, 0xbfb8aa3b, v153
	v_exp_f32_e32 v153, v153
	v_rcp_f32_e32 v179, v154
	v_mul_f32_e32 v155, 0xbfb8aa3b, v155
	v_exp_f32_e32 v155, v155
	v_add_f32_e32 v153, 1.0, v153
	v_rcp_f32_e32 v153, v153
	v_mul_f32_e32 v176, 0xbfb8aa3b, v176
	v_add_f32_e32 v155, 1.0, v155
	v_rcp_f32_e32 v180, v155
	v_mul_f32_e32 v153, v154, v153
	v_add_f32_e32 v154, v28, v136
	v_mul_f32_e32 v154, 0xbfb8aa3b, v154
	v_exp_f32_e32 v154, v154
	v_exp_f32_e32 v176, v176
	v_add_f32_e32 v177, v22, v134
	v_mul_f32_e32 v177, 0xbfb8aa3b, v177
	v_add_f32_e32 v154, 1.0, v154
	v_rcp_f32_e32 v154, v154
	v_add_f32_e32 v176, 1.0, v176
	v_rcp_f32_e32 v181, v176
	v_exp_f32_e32 v177, v177
	v_mul_f32_e32 v154, v155, v154
	v_add_f32_e32 v155, v29, v137
	v_mul_f32_e32 v155, 0xbfb8aa3b, v155
	v_exp_f32_e32 v155, v155
	v_add_f32_e32 v177, 1.0, v177
	v_rcp_f32_e32 v182, v177
	v_add_f32_e32 v144, v16, v144
	v_add_f32_e32 v155, 1.0, v155
	v_rcp_f32_e32 v155, v155
	v_add_f32_e32 v183, v23, v135
	v_mul_f32_e32 v144, 0xbfb8aa3b, v144
	v_mul_f32_e32 v183, 0xbfb8aa3b, v183
	v_mul_f32_e32 v155, v176, v155
	v_add_f32_e32 v176, v30, v138
	v_mul_f32_e32 v176, 0xbfb8aa3b, v176
	v_exp_f32_e32 v176, v176
	v_exp_f32_e32 v144, v144
	v_exp_f32_e32 v183, v183
	v_add_f32_e32 v140, v8, v140
	v_add_f32_e32 v176, 1.0, v176
	v_rcp_f32_e32 v176, v176
	v_mul_f32_e32 v140, 0xbfb8aa3b, v140
	v_add_f32_e32 v144, 1.0, v144
	v_exp_f32_e32 v140, v140
	v_mul_f32_e32 v176, v177, v176
	v_add_f32_e32 v177, v31, v139
	v_mul_f32_e32 v177, 0xbfb8aa3b, v177
	v_exp_f32_e32 v177, v177
	v_add_f32_e32 v183, 1.0, v183
	v_rcp_f32_e32 v144, v144
	v_cvt_pk_bf16_f32 v150, v150, v151
	v_add_f32_e32 v177, 1.0, v177
	v_rcp_f32_e32 v177, v177
	v_cvt_pk_bf16_f32 v151, v152, v153
	v_cvt_pk_bf16_f32 v152, v154, v155
	v_lshl_add_u64 v[154:155], v[148:149], 0, s[18:19]
	v_mul_f32_e32 v177, v183, v177
	v_cvt_pk_bf16_f32 v153, v176, v177
	v_lshl_add_u64 v[176:177], s[44:45], 0, v[154:155]
	global_store_dwordx4 v[176:177], v[150:153], off
	v_lshl_add_u64 v[154:155], s[46:47], 0, v[154:155]
	v_add_f32_e32 v140, 1.0, v140
	v_cvt_pk_bf16_f32 v150, v160, v175
	v_rcp_f32_e32 v184, v183
	v_cvt_pk_bf16_f32 v151, v178, v179
	v_cvt_pk_bf16_f32 v152, v180, v181
	v_cvt_pk_bf16_f32 v153, v182, v184
	global_store_dwordx4 v[154:155], v[150:153], off
	v_add_f32_e32 v141, v9, v141
	v_mul_f32_e32 v141, 0xbfb8aa3b, v141
	v_rcp_f32_e32 v150, v140
	v_mul_f32_e32 v140, v140, v144
	v_add_f32_e32 v144, v17, v145
	v_mul_f32_e32 v144, 0xbfb8aa3b, v144
	v_exp_f32_e32 v144, v144
	v_exp_f32_e32 v141, v141
	v_add_f32_e32 v142, v10, v142
	v_mul_f32_e32 v142, 0xbfb8aa3b, v142
	v_add_f32_e32 v144, 1.0, v144
	v_rcp_f32_e32 v144, v144
	v_add_f32_e32 v141, 1.0, v141
	v_rcp_f32_e32 v145, v141
	v_exp_f32_e32 v142, v142
	v_mul_f32_e32 v141, v141, v144
	v_add_f32_e32 v144, v18, v146
	v_mul_f32_e32 v144, 0xbfb8aa3b, v144
	v_exp_f32_e32 v144, v144
	v_add_f32_e32 v142, 1.0, v142
	v_rcp_f32_e32 v146, v142
	v_add_f32_e32 v136, v12, v136
	v_add_f32_e32 v144, 1.0, v144
	v_rcp_f32_e32 v144, v144
	v_mul_f32_e32 v136, 0xbfb8aa3b, v136
	v_exp_f32_e32 v136, v136
	v_add_f32_e32 v143, v11, v143
	v_mul_f32_e32 v142, v142, v144
	v_add_f32_e32 v144, v19, v147
	v_mul_f32_e32 v144, 0xbfb8aa3b, v144
	v_exp_f32_e32 v144, v144
	v_add_f32_e32 v132, v4, v132
	v_mul_f32_e32 v143, 0xbfb8aa3b, v143
	v_mul_f32_e32 v132, 0xbfb8aa3b, v132
	v_add_f32_e32 v144, 1.0, v144
	v_exp_f32_e32 v143, v143
	v_add_f32_e32 v136, 1.0, v136
	v_exp_f32_e32 v132, v132
	v_rcp_f32_e32 v144, v144
	v_rcp_f32_e32 v136, v136
	v_add_f32_e32 v143, 1.0, v143
	v_add_f32_e32 v132, 1.0, v132
	v_rcp_f32_e32 v147, v143
	v_mul_f32_e32 v143, v143, v144
	v_rcp_f32_e32 v144, v132
	v_mul_f32_e32 v136, v132, v136
	v_add_f32_e32 v132, v13, v137
	v_mul_f32_e32 v132, 0xbfb8aa3b, v132
	v_exp_f32_e32 v132, v132
	v_add_f32_e32 v133, v5, v133
	v_mul_f32_e32 v133, 0xbfb8aa3b, v133
	v_exp_f32_e32 v133, v133
	v_add_f32_e32 v132, 1.0, v132
	v_rcp_f32_e32 v132, v132
	v_add_f32_e32 v133, 1.0, v133
	v_rcp_f32_e32 v151, v133
	v_mul_f32_e32 v137, v133, v132
	v_add_f32_e32 v132, v14, v138
	v_mul_f32_e32 v132, 0xbfb8aa3b, v132
	v_exp_f32_e32 v132, v132
	v_add_f32_e32 v133, v6, v134
	v_mul_f32_e32 v133, 0xbfb8aa3b, v133
	v_exp_f32_e32 v133, v133
	v_add_f32_e32 v132, 1.0, v132
	v_rcp_f32_e32 v132, v132
	v_add_f32_e32 v133, 1.0, v133
	v_rcp_f32_e32 v152, v133
	v_mul_f32_e32 v138, v133, v132
	v_add_f32_e32 v132, v15, v139
	v_mul_f32_e32 v132, 0xbfb8aa3b, v132
	v_exp_f32_e32 v132, v132
	v_add_f32_e32 v133, v7, v135
	v_mul_f32_e32 v133, 0xbfb8aa3b, v133
	v_exp_f32_e32 v133, v133
	v_add_f32_e32 v132, 1.0, v132
	v_rcp_f32_e32 v132, v132
	v_add_f32_e32 v133, 1.0, v133
	v_rcp_f32_e32 v153, v133
	v_mul_f32_e32 v135, v133, v132
	v_cvt_pk_bf16_f32 v132, v140, v141
	v_cvt_pk_bf16_f32 v133, v142, v143
	v_cvt_pk_bf16_f32 v134, v136, v137
	v_lshl_add_u64 v[136:137], v[148:149], 0, s[4:5]
	v_cvt_pk_bf16_f32 v135, v138, v135
	v_lshl_add_u64 v[138:139], s[44:45], 0, v[136:137]
	v_lshl_add_u64 v[136:137], s[46:47], 0, v[136:137]
	global_store_dwordx4 v[138:139], v[132:135], off
	s_nop 1
	v_cvt_pk_bf16_f32 v132, v150, v145
	v_cvt_pk_bf16_f32 v133, v146, v147
	v_cvt_pk_bf16_f32 v134, v144, v151
	v_cvt_pk_bf16_f32 v135, v152, v153
	global_store_dwordx4 v[136:137], v[132:135], off
	s_cbranch_execz .LBB0_391

.LBB0_391:
	s_lshl_b32 s4, s96, 8
	s_or_b32 s67, s4, s85
	v_or_b32_e32 v176, s67, v191
	v_ashrrev_i32_e32 v177, 31, v176
	v_or_b32_e32 v136, s85, v191
	v_lshlrev_b32_e32 v136, 2, v136
	v_add_u32_e32 v136, 0x27500, v136
	ds_read_b128 v[140:143], v136 offset:16
	ds_read_b128 v[144:147], v136
	ds_read_b128 v[132:135], v136 offset:144
	ds_read_b128 v[136:139], v136 offset:128
	s_cmp_gt_i32 s96, 1
	s_mov_b64 s[4:5], -1
	s_cbranch_scc0 .LBB0_469
	s_cmp_gt_u32 s96, 3
	s_cbranch_scc0 .LBB0_450
	s_cmp_gt_u32 s96, 5
	s_cbranch_scc0 .LBB0_431
	s_cmp_lt_u32 s96, 10
	s_cbranch_scc1 .LBB0_412
	s_waitcnt lgkmcnt(0)
	v_pk_add_f32 v[150:151], v[128:129], v[144:145]
	v_pk_add_f32 v[154:155], v[124:125], v[140:141]
	v_mul_f32_e32 v160, 0x3d372713, v150
	v_mul_f32_e32 v160, v150, v160
	v_fma_f32 v160, v150, v160, v150
	v_mul_f32_e32 v160, 0x3fcc422a, v160
	v_mul_f32_e32 v160, 0xbfb8aa3b, v160
	v_exp_f32_e32 v160, v160
	v_mov_b64_e32 v[148:149], s[30:31]
	v_mad_i64_i32 v[148:149], s[4:5], v174, s13, v[148:149]
	v_add_f32_e32 v160, 1.0, v160
	v_rcp_f32_e32 v160, v160
	v_lshl_add_u64 v[178:179], v[176:177], 1, v[148:149]
	v_pk_add_f32 v[148:149], v[130:131], v[146:147]
	v_pk_add_f32 v[152:153], v[126:127], v[142:143]
	v_mul_f32_e32 v150, v150, v160
	v_mul_f32_e32 v160, 0x3d372713, v154
	v_mul_f32_e32 v160, v154, v160
	v_fma_f32 v160, v154, v160, v154
	v_mul_f32_e32 v160, 0x3fcc422a, v160
	v_mul_f32_e32 v160, 0xbfb8aa3b, v160
	v_exp_f32_e32 v160, v160
	s_movk_i32 s34, 0xf000
	s_movk_i32 s38, 0x9040
	s_mov_b32 s35, -1
	v_add_f32_e32 v160, 1.0, v160
	v_rcp_f32_e32 v160, v160
	s_mov_b32 s39, -1
	v_lshl_add_u64 v[182:183], v[178:179], 0, s[38:39]
	v_mul_f32_e32 v154, v154, v160
	v_mul_f32_e32 v160, 0x3d372713, v151
	v_mul_f32_e32 v160, v151, v160
	v_fma_f32 v160, v151, v160, v151
	v_mul_f32_e32 v160, 0x3fcc422a, v160
	v_mul_f32_e32 v160, 0xbfb8aa3b, v160
	v_exp_f32_e32 v160, v160
	s_nop 0
	v_add_f32_e32 v160, 1.0, v160
	v_rcp_f32_e32 v160, v160
	s_nop 0
	v_mul_f32_e32 v151, v151, v160
	v_mul_f32_e32 v160, 0x3d372713, v155
	v_mul_f32_e32 v160, v155, v160
	v_fma_f32 v160, v155, v160, v155
	v_mul_f32_e32 v160, 0x3fcc422a, v160
	v_mul_f32_e32 v160, 0xbfb8aa3b, v160
	v_exp_f32_e32 v160, v160
	s_nop 0
	v_add_f32_e32 v160, 1.0, v160
	v_rcp_f32_e32 v160, v160
	s_nop 0
	v_mul_f32_e32 v155, v155, v160
	v_mul_f32_e32 v160, 0x3d372713, v148
	v_mul_f32_e32 v160, v148, v160
	v_fma_f32 v160, v148, v160, v148
	v_mul_f32_e32 v160, 0x3fcc422a, v160
	v_mul_f32_e32 v160, 0xbfb8aa3b, v160
	v_exp_f32_e32 v160, v160
	s_nop 0
	v_add_f32_e32 v160, 1.0, v160
	v_rcp_f32_e32 v160, v160
	s_nop 0
	v_mul_f32_e32 v148, v148, v160
	v_mul_f32_e32 v160, 0x3d372713, v152
	v_mul_f32_e32 v160, v152, v160
	v_fma_f32 v160, v152, v160, v152
	v_mul_f32_e32 v160, 0x3fcc422a, v160
	v_mul_f32_e32 v160, 0xbfb8aa3b, v160
	v_exp_f32_e32 v160, v160
	s_nop 0
	v_add_f32_e32 v160, 1.0, v160
	v_rcp_f32_e32 v160, v160
	s_nop 0
	v_mul_f32_e32 v152, v152, v160
	v_mul_f32_e32 v160, 0x3d372713, v149
	v_mul_f32_e32 v160, v149, v160
	v_fma_f32 v160, v149, v160, v149
	v_mul_f32_e32 v160, 0x3fcc422a, v160
	v_mul_f32_e32 v160, 0xbfb8aa3b, v160
	v_exp_f32_e32 v160, v160
	s_nop 0
	v_add_f32_e32 v160, 1.0, v160
	v_rcp_f32_e32 v160, v160
	s_nop 0
	v_mul_f32_e32 v149, v149, v160
	v_mul_f32_e32 v160, 0x3d372713, v153
	v_mul_f32_e32 v160, v153, v160
	v_fma_f32 v160, v153, v160, v153
	v_mul_f32_e32 v160, 0x3fcc422a, v160
	v_mul_f32_e32 v160, 0xbfb8aa3b, v160
	v_exp_f32_e32 v160, v160
	s_nop 0
	v_add_f32_e32 v160, 1.0, v160
	v_rcp_f32_e32 v160, v160
	s_nop 0
	v_mul_f32_e32 v153, v153, v160
	v_cvt_pk_bf16_f32 v160, v150, v151
	v_pk_add_f32 v[150:151], v[120:121], v[136:137]
	v_cvt_pk_bf16_f32 v175, v148, v149
	v_cvt_pk_bf16_f32 v184, v154, v155
	v_pk_add_f32 v[154:155], v[116:117], v[132:133]
	v_mul_f32_e32 v180, 0x3d372713, v150
	v_mul_f32_e32 v180, v150, v180
	v_fma_f32 v180, v150, v180, v150
	v_mul_f32_e32 v180, 0x3fcc422a, v180
	v_mul_f32_e32 v180, 0xbfb8aa3b, v180
	v_exp_f32_e32 v180, v180
	v_pk_add_f32 v[148:149], v[122:123], v[138:139]
	v_cvt_pk_bf16_f32 v185, v152, v153
	v_pk_add_f32 v[152:153], v[118:119], v[134:135]
	v_add_f32_e32 v180, 1.0, v180
	v_rcp_f32_e32 v180, v180
	s_nop 0
	v_mul_f32_e32 v150, v150, v180
	v_mul_f32_e32 v180, 0x3d372713, v154
	v_mul_f32_e32 v180, v154, v180
	v_fma_f32 v180, v154, v180, v154
	v_mul_f32_e32 v180, 0x3fcc422a, v180
	v_mul_f32_e32 v180, 0xbfb8aa3b, v180
	v_exp_f32_e32 v180, v180
	s_nop 0
	v_add_f32_e32 v180, 1.0, v180
	v_rcp_f32_e32 v180, v180
	s_nop 0
	v_mul_f32_e32 v154, v154, v180
	v_mul_f32_e32 v180, 0x3d372713, v151
	v_mul_f32_e32 v180, v151, v180
	v_fma_f32 v180, v151, v180, v151
	v_mul_f32_e32 v180, 0x3fcc422a, v180
	v_mul_f32_e32 v180, 0xbfb8aa3b, v180
	v_exp_f32_e32 v180, v180
	s_nop 0
	v_add_f32_e32 v180, 1.0, v180
	v_rcp_f32_e32 v180, v180
	s_nop 0
	v_mul_f32_e32 v151, v151, v180
	v_mul_f32_e32 v180, 0x3d372713, v155
	v_mul_f32_e32 v180, v155, v180
	v_fma_f32 v180, v155, v180, v155
	v_mul_f32_e32 v180, 0x3fcc422a, v180
	v_mul_f32_e32 v180, 0xbfb8aa3b, v180
	v_exp_f32_e32 v180, v180
	v_cvt_pk_bf16_f32 v150, v150, v151
	s_nop 0
	v_add_f32_e32 v180, 1.0, v180
	v_rcp_f32_e32 v180, v180
	s_nop 0
	v_mul_f32_e32 v155, v155, v180
	v_mul_f32_e32 v180, 0x3d372713, v148
	v_mul_f32_e32 v180, v148, v180
	v_fma_f32 v180, v148, v180, v148
	v_mul_f32_e32 v180, 0x3fcc422a, v180
	v_mul_f32_e32 v180, 0xbfb8aa3b, v180
	v_exp_f32_e32 v180, v180
	s_nop 0
	v_add_f32_e32 v180, 1.0, v180
	v_rcp_f32_e32 v180, v180
	s_nop 0
	v_mul_f32_e32 v148, v148, v180
	v_mul_f32_e32 v180, 0x3d372713, v152
	v_mul_f32_e32 v180, v152, v180
	v_fma_f32 v180, v152, v180, v152
	v_mul_f32_e32 v180, 0x3fcc422a, v180
	v_mul_f32_e32 v180, 0xbfb8aa3b, v180
	v_exp_f32_e32 v180, v180
	s_nop 0
	v_add_f32_e32 v180, 1.0, v180
	v_rcp_f32_e32 v180, v180
	s_nop 0
	v_mul_f32_e32 v152, v152, v180
	v_mul_f32_e32 v180, 0x3d372713, v149
	v_mul_f32_e32 v180, v149, v180
	v_fma_f32 v180, v149, v180, v149
	v_mul_f32_e32 v180, 0x3fcc422a, v180
	v_mul_f32_e32 v180, 0xbfb8aa3b, v180
	v_exp_f32_e32 v180, v180
	s_nop 0
	v_add_f32_e32 v180, 1.0, v180
	v_rcp_f32_e32 v180, v180
	s_nop 0
	v_mul_f32_e32 v149, v149, v180
	v_mul_f32_e32 v180, 0x3d372713, v153
	v_mul_f32_e32 v180, v153, v180
	v_fma_f32 v180, v153, v180, v153
	v_mul_f32_e32 v180, 0x3fcc422a, v180
	v_mul_f32_e32 v180, 0xbfb8aa3b, v180
	v_exp_f32_e32 v180, v180
	v_cvt_pk_bf16_f32 v151, v148, v149
	v_mov_b32_e32 v148, 0
	v_mov_b32_e32 v149, 0
	v_add_f32_e32 v180, 1.0, v180
	v_rcp_f32_e32 v180, v180
	v_cvt_pk_bf16_f32 v154, v154, v155
	v_mov_b32_dpp v148, v150 row_ror:8 row_mask:0xf bank_mask:0xf
	v_mov_b32_dpp v149, v151 row_ror:8 row_mask:0xf bank_mask:0xf
	v_mul_f32_e32 v153, v153, v180
	v_cvt_pk_bf16_f32 v152, v152, v153
	v_mov_b32_e32 v150, 0
	v_mov_b32_e32 v151, 0
	v_lshl_add_u64 v[180:181], v[178:179], 0, s[34:35]
	v_mov_b32_dpp v150, v154 row_ror:8 row_mask:0xf bank_mask:0xf
	v_mov_b32_dpp v151, v152 row_ror:8 row_mask:0xf bank_mask:0xf
	v_mov_b32_e32 v152, v160
	v_mov_b32_e32 v153, v175
	v_mov_b32_e32 v154, v184
	v_mov_b32_e32 v155, v185
	s_and_saveexec_b64 s[4:5], s[6:7]
	s_mov_b64 s[82:83], 0x5040
	s_cbranch_execz .LBB0_397
	v_lshl_add_u64 v[178:179], v[178:179], 0, s[82:83]
	v_mov_b64_e32 v[182:183], v[180:181]
	v_mov_b32_e32 v152, v148
	v_mov_b32_e32 v153, v149
	v_mov_b32_e32 v154, v150
	v_mov_b32_e32 v155, v151
	v_mov_b32_e32 v148, v160
	v_mov_b32_e32 v149, v175
	v_mov_b32_e32 v150, v184
	v_mov_b32_e32 v151, v185
	v_mov_b64_e32 v[180:181], v[178:179]

.LBB0_412:
	s_and_b64 vcc, exec, s[4:5]
	s_cbranch_vccz .LBB0_430
	s_add_i32 s4, s67, 0xfffffa00
	s_ashr_i32 s34, s4, 6
	s_ashr_i32 s4, s29, 7
	s_and_b32 s4, s4, 0x3ffffff0
	s_add_i32 s4, s4, s34
	s_mulk_i32 s4, 0x804
	v_and_b32_e32 v148, 0x7cf, v174
	v_add3_u32 v178, v148, s4, 2
	v_ashrrev_i32_e32 v179, 31, v178
	v_lshlrev_b64 v[148:149], 7, v[178:179]
	v_lshl_add_u64 v[180:181], v[162:163], 0, v[148:149]
	s_waitcnt lgkmcnt(0)
	v_pk_add_f32 v[148:149], v[130:131], v[146:147]
	v_pk_add_f32 v[150:151], v[128:129], v[144:145]
	v_pk_add_f32 v[152:153], v[126:127], v[142:143]
	v_pk_add_f32 v[154:155], v[124:125], v[140:141]
	v_cvt_pk_bf16_f32 v160, v150, v151
	v_cvt_pk_bf16_f32 v175, v148, v149
	v_pk_add_f32 v[148:149], v[122:123], v[138:139]
	v_pk_add_f32 v[150:151], v[120:121], v[136:137]
	v_cvt_pk_bf16_f32 v179, v154, v155
	v_cvt_pk_bf16_f32 v184, v152, v153
	v_pk_add_f32 v[152:153], v[118:119], v[134:135]
	v_pk_add_f32 v[154:155], v[116:117], v[132:133]
	v_cvt_pk_bf16_f32 v150, v150, v151
	v_cvt_pk_bf16_f32 v151, v148, v149
	v_mov_b32_e32 v148, 0
	v_mov_b32_e32 v149, 0
	v_cvt_pk_bf16_f32 v154, v154, v155
	v_cvt_pk_bf16_f32 v152, v152, v153
	v_lshl_add_u64 v[182:183], v[180:181], 0, s[68:69]
	v_mov_b32_dpp v148, v150 row_ror:8 row_mask:0xf bank_mask:0xf
	v_mov_b32_dpp v149, v151 row_ror:8 row_mask:0xf bank_mask:0xf
	v_mov_b32_e32 v150, 0
	v_mov_b32_e32 v151, 0
	v_mov_b32_e32 v153, v175
	v_mov_b32_dpp v150, v154 row_ror:8 row_mask:0xf bank_mask:0xf
	v_mov_b32_dpp v151, v152 row_ror:8 row_mask:0xf bank_mask:0xf
	v_mov_b32_e32 v152, v160
	v_mov_b32_e32 v154, v179
	v_mov_b32_e32 v155, v184
	s_and_saveexec_b64 s[4:5], s[6:7]
	s_mov_b64 s[38:39], 0x440
	s_cbranch_execz .LBB0_415
	v_lshl_add_u64 v[218:219], v[180:181], 0, s[38:39]
	v_mov_b64_e32 v[182:183], v[180:181]
	v_mov_b32_e32 v152, v148
	v_mov_b32_e32 v153, v149
	v_mov_b32_e32 v154, v150
	v_mov_b32_e32 v155, v151
	v_mov_b32_e32 v148, v160
	v_mov_b32_e32 v149, v175
	v_mov_b32_e32 v150, v179
	v_mov_b32_e32 v151, v184
	v_mov_b64_e32 v[180:181], v[218:219]

.LBB0_431:
	s_andn2_b64 vcc, exec, s[4:5]
	s_cbranch_vccnz .LBB0_449
	s_add_i32 s4, s67, 0xfffffc00
	s_ashr_i32 s34, s4, 6
	s_lshr_b32 s4, s29, 8
	s_and_b32 s4, s4, 0x1ffff8
	s_add_i32 s4, s4, s34
	v_and_b32_e32 v148, 0x7cf, v174
	v_lshl_or_b32 v178, s4, 11, v148
	v_ashrrev_i32_e32 v179, 31, v178
	v_lshlrev_b64 v[148:149], 7, v[178:179]
	v_lshl_add_u64 v[180:181], v[164:165], 0, v[148:149]
	s_waitcnt lgkmcnt(0)
	v_pk_add_f32 v[148:149], v[130:131], v[146:147]
	v_pk_add_f32 v[150:151], v[128:129], v[144:145]
	v_pk_add_f32 v[152:153], v[126:127], v[142:143]
	v_pk_add_f32 v[154:155], v[124:125], v[140:141]
	v_cvt_pk_bf16_f32 v160, v150, v151
	v_cvt_pk_bf16_f32 v175, v148, v149
	v_pk_add_f32 v[148:149], v[122:123], v[138:139]
	v_pk_add_f32 v[150:151], v[120:121], v[136:137]
	v_cvt_pk_bf16_f32 v179, v154, v155
	v_cvt_pk_bf16_f32 v184, v152, v153
	v_pk_add_f32 v[152:153], v[118:119], v[134:135]
	v_pk_add_f32 v[154:155], v[116:117], v[132:133]
	v_cvt_pk_bf16_f32 v150, v150, v151
	v_cvt_pk_bf16_f32 v151, v148, v149
	v_mov_b32_e32 v148, 0
	v_mov_b32_e32 v149, 0
	v_cvt_pk_bf16_f32 v154, v154, v155
	v_cvt_pk_bf16_f32 v152, v152, v153
	v_lshl_add_u64 v[182:183], v[180:181], 0, s[68:69]
	v_mov_b32_dpp v148, v150 row_ror:8 row_mask:0xf bank_mask:0xf
	v_mov_b32_dpp v149, v151 row_ror:8 row_mask:0xf bank_mask:0xf
	v_mov_b32_e32 v150, 0
	v_mov_b32_e32 v151, 0
	v_mov_b32_e32 v153, v175
	v_mov_b32_dpp v150, v154 row_ror:8 row_mask:0xf bank_mask:0xf
	v_mov_b32_dpp v151, v152 row_ror:8 row_mask:0xf bank_mask:0xf
	v_mov_b32_e32 v152, v160
	v_mov_b32_e32 v154, v179
	v_mov_b32_e32 v155, v184
	s_and_saveexec_b64 s[4:5], s[6:7]
	s_mov_b64 s[38:39], 0x440
	s_cbranch_execz .LBB0_434
	v_lshl_add_u64 v[218:219], v[180:181], 0, s[38:39]
	v_mov_b64_e32 v[182:183], v[180:181]
	v_mov_b32_e32 v152, v148
	v_mov_b32_e32 v153, v149
	v_mov_b32_e32 v154, v150
	v_mov_b32_e32 v155, v151
	v_mov_b32_e32 v148, v160
	v_mov_b32_e32 v149, v175
	v_mov_b32_e32 v150, v179
	v_mov_b32_e32 v151, v184
	v_mov_b64_e32 v[180:181], v[218:219]

.LBB0_450:
	s_andn2_b64 vcc, exec, s[4:5]
	s_cbranch_vccnz .LBB0_468
	s_addk_i32 s67, 0xfe00
	s_lshr_b32 s4, s29, 8
	s_ashr_i32 s34, s67, 6
	s_and_b32 s4, s4, 0x1ffff8
	s_add_i32 s4, s4, s34
	v_and_b32_e32 v148, 0x7cf, v174
	v_lshl_or_b32 v178, s4, 11, v148
	v_ashrrev_i32_e32 v179, 31, v178
	v_lshlrev_b64 v[148:149], 7, v[178:179]
	v_lshl_add_u64 v[180:181], v[166:167], 0, v[148:149]
	s_waitcnt lgkmcnt(0)
	v_pk_add_f32 v[148:149], v[130:131], v[146:147]
	v_pk_add_f32 v[150:151], v[128:129], v[144:145]
	v_pk_add_f32 v[152:153], v[126:127], v[142:143]
	v_pk_add_f32 v[154:155], v[124:125], v[140:141]
	v_cvt_pk_bf16_f32 v160, v150, v151
	v_cvt_pk_bf16_f32 v175, v148, v149
	v_pk_add_f32 v[148:149], v[122:123], v[138:139]
	v_pk_add_f32 v[150:151], v[120:121], v[136:137]
	v_cvt_pk_bf16_f32 v179, v154, v155
	v_cvt_pk_bf16_f32 v184, v152, v153
	v_pk_add_f32 v[152:153], v[118:119], v[134:135]
	v_pk_add_f32 v[154:155], v[116:117], v[132:133]
	v_cvt_pk_bf16_f32 v150, v150, v151
	v_cvt_pk_bf16_f32 v151, v148, v149
	v_mov_b32_e32 v148, 0
	v_mov_b32_e32 v149, 0
	v_cvt_pk_bf16_f32 v154, v154, v155
	v_cvt_pk_bf16_f32 v152, v152, v153
	v_lshl_add_u64 v[182:183], v[180:181], 0, s[68:69]
	v_mov_b32_dpp v148, v150 row_ror:8 row_mask:0xf bank_mask:0xf
	v_mov_b32_dpp v149, v151 row_ror:8 row_mask:0xf bank_mask:0xf
	v_mov_b32_e32 v150, 0
	v_mov_b32_e32 v151, 0
	v_mov_b32_e32 v153, v175
	v_mov_b32_dpp v150, v154 row_ror:8 row_mask:0xf bank_mask:0xf
	v_mov_b32_dpp v151, v152 row_ror:8 row_mask:0xf bank_mask:0xf
	v_mov_b32_e32 v152, v160
	v_mov_b32_e32 v154, v179
	v_mov_b32_e32 v155, v184
	s_and_saveexec_b64 s[4:5], s[6:7]
	s_mov_b64 s[38:39], 0x440
	s_cbranch_execz .LBB0_453
	v_lshl_add_u64 v[218:219], v[180:181], 0, s[38:39]
	v_mov_b64_e32 v[182:183], v[180:181]
	v_mov_b32_e32 v152, v148
	v_mov_b32_e32 v153, v149
	v_mov_b32_e32 v154, v150
	v_mov_b32_e32 v155, v151
	v_mov_b32_e32 v148, v160
	v_mov_b32_e32 v149, v175
	v_mov_b32_e32 v150, v179
	v_mov_b32_e32 v151, v184
	v_mov_b64_e32 v[180:181], v[218:219]

.LBB0_469:
	s_andn2_b64 vcc, exec, s[4:5]
	s_cbranch_vccnz .LBB0_487
	v_mov_b64_e32 v[148:149], s[30:31]
	s_waitcnt lgkmcnt(0)
	v_pk_add_f32 v[128:129], v[128:129], v[144:145]
	v_pk_add_f32 v[122:123], v[122:123], v[138:139]
	v_pk_add_f32 v[120:121], v[120:121], v[136:137]
	v_pk_add_f32 v[118:119], v[118:119], v[134:135]
	v_pk_add_f32 v[116:117], v[116:117], v[132:133]
	v_mad_i64_i32 v[148:149], s[4:5], v174, s13, v[148:149]
	v_pk_add_f32 v[130:131], v[130:131], v[146:147]
	v_pk_mul_f32 v[128:129], v[128:129], s[72:73] op_sel_hi:[1,0]
	v_pk_add_f32 v[126:127], v[126:127], v[142:143]
	v_pk_add_f32 v[124:125], v[124:125], v[140:141]
	v_pk_mul_f32 v[122:123], v[122:123], s[72:73] op_sel_hi:[1,0]
	v_pk_mul_f32 v[120:121], v[120:121], s[72:73] op_sel_hi:[1,0]
	v_pk_mul_f32 v[118:119], v[118:119], s[72:73] op_sel_hi:[1,0]
	v_pk_mul_f32 v[116:117], v[116:117], s[72:73] op_sel_hi:[1,0]
	v_lshl_add_u64 v[148:149], v[176:177], 1, v[148:149]
	v_pk_mul_f32 v[130:131], v[130:131], s[72:73] op_sel_hi:[1,0]
	v_pk_mul_f32 v[150:151], v[126:127], s[72:73] op_sel_hi:[1,0]
	v_pk_mul_f32 v[124:125], v[124:125], s[72:73] op_sel_hi:[1,0]
	v_cvt_pk_bf16_f32 v126, v128, v129
	v_cvt_pk_bf16_f32 v127, v130, v131
	s_nop 0
	v_cvt_pk_bf16_f32 v128, v124, v125
	v_cvt_pk_bf16_f32 v129, v150, v151
	v_cvt_pk_bf16_f32 v120, v120, v121
	v_cvt_pk_bf16_f32 v121, v122, v123
	v_cvt_pk_bf16_f32 v122, v116, v117
	v_cvt_pk_bf16_f32 v123, v118, v119
	v_mov_b32_e32 v116, 0
	v_mov_b32_e32 v117, 0
	v_mov_b32_e32 v118, 0
	v_mov_b32_e32 v119, 0
	v_mov_b32_dpp v116, v120 row_ror:8 row_mask:0xf bank_mask:0xf
	v_mov_b32_dpp v117, v121 row_ror:8 row_mask:0xf bank_mask:0xf
	v_mov_b32_dpp v118, v122 row_ror:8 row_mask:0xf bank_mask:0xf
	v_mov_b32_dpp v119, v123 row_ror:8 row_mask:0xf bank_mask:0xf
	v_lshl_add_u64 v[124:125], v[148:149], 0, s[92:93]
	v_mov_b32_e32 v120, v126
	v_mov_b32_e32 v121, v127
	v_mov_b32_e32 v122, v128
	v_mov_b32_e32 v123, v129
	s_and_saveexec_b64 s[4:5], s[6:7]
	s_mov_b64 s[34:35], 0x6040
	s_cbranch_execz .LBB0_472
	v_lshl_add_u64 v[130:131], v[148:149], 0, s[34:35]
	v_mov_b64_e32 v[124:125], v[148:149]
	v_mov_b32_e32 v120, v116
	v_mov_b32_e32 v121, v117
	v_mov_b32_e32 v122, v118
	v_mov_b32_e32 v123, v119
	v_mov_b32_e32 v116, v126
	v_mov_b32_e32 v117, v127
	v_mov_b32_e32 v118, v128
	v_mov_b32_e32 v119, v129
	v_mov_b64_e32 v[148:149], v[130:131]
